# attention: removed redundant negm copies (MFMA reads negm directly as C)
# baseline (speedup 1.0000x reference)
.LBB0_517:
	ds_read_b128 v[112:115], v165 offset:9216
	ds_read_b128 v[116:119], v165 offset:9248
	v_exp_f32_e32 v206, v48
	v_exp_f32_e32 v208, v49
	v_exp_f32_e32 v210, v50
	v_exp_f32_e32 v212, v51
	v_exp_f32_e32 v214, v52
	v_exp_f32_e32 v216, v53
	v_exp_f32_e32 v218, v54
	s_waitcnt lgkmcnt(1)
	v_mfma_f32_32x32x16_bf16 v[96:111], v[112:115], v[130:133], v[32:47]
	ds_read_b128 v[178:181], v165 offset:13824
	ds_read_b128 v[182:185], v165 offset:13856
	ds_read_b128 v[112:115], v165 offset:9280
	ds_read_b128 v[194:197], v165 offset:9312
	ds_read_b128 v[198:201], v165 offset:13888
	ds_read_b128 v[202:205], v165 offset:13920
	v_exp_f32_e32 v220, v55
	ds_read_b64_tr_b16 v[48:49], v175 offset:18432
	ds_read_b64_tr_b16 v[50:51], v175 offset:19968
	ds_read_b64_tr_b16 v[54:55], v175 offset:20032
	ds_read_b64_tr_b16 v[52:53], v175 offset:18496
	v_exp_f32_e32 v222, v66
	v_exp_f32_e32 v224, v67
	v_cvt_pk_bf16_f32 v66, v214, v216
	v_cvt_pk_bf16_f32 v67, v218, v220
	s_waitcnt lgkmcnt(10)
	v_mfma_f32_32x32x16_bf16 v[96:111], v[116:119], v[134:137], v[96:111]
	v_exp_f32_e32 v207, v56
	v_exp_f32_e32 v209, v57
	v_exp_f32_e32 v211, v58
	v_exp_f32_e32 v213, v59
	v_exp_f32_e32 v215, v60
	v_exp_f32_e32 v217, v61
	v_exp_f32_e32 v219, v62
	s_waitcnt lgkmcnt(7)
	v_mfma_f32_32x32x16_bf16 v[96:111], v[112:115], v[138:141], v[96:111]
	s_waitcnt lgkmcnt(6)
	v_mfma_f32_32x32x16_bf16 v[96:111], v[194:197], v[150:153], v[96:111]
	v_exp_f32_e32 v221, v63
	v_exp_f32_e32 v226, v68
	v_exp_f32_e32 v228, v69
	v_exp_f32_e32 v223, v74
	v_exp_f32_e32 v225, v75
	v_exp_f32_e32 v227, v76
	v_exp_f32_e32 v229, v77
	v_mfma_f32_32x32x16_bf16 v[112:127], v[178:181], v[130:133], v[32:47]
	v_exp_f32_e32 v178, v64
	v_exp_f32_e32 v180, v65
	v_cvt_pk_bf16_f32 v64, v206, v208
	v_cvt_pk_bf16_f32 v65, v210, v212
	v_exp_f32_e32 v179, v72
	v_exp_f32_e32 v181, v73
	ds_read_b64_tr_b16 v[56:57], v175 offset:21504
	ds_read_b64_tr_b16 v[58:59], v175 offset:23040
	ds_read_b64_tr_b16 v[62:63], v175 offset:23104
	ds_read_b64_tr_b16 v[60:61], v175 offset:21568
	v_mfma_f32_32x32x16_bf16 v[112:127], v[182:185], v[134:137], v[112:127]
	v_exp_f32_e32 v182, v70
	v_exp_f32_e32 v184, v71
	v_exp_f32_e32 v183, v78
	v_exp_f32_e32 v185, v79
	v_pk_add_f32 v[194:195], v[206:207], v[208:209]
	v_pk_add_f32 v[196:197], v[210:211], v[212:213]
	v_cvt_pk_bf16_f32 v68, v207, v209
	s_waitcnt lgkmcnt(9)
	v_mfma_f32_32x32x16_bf16 v[112:127], v[198:201], v[138:141], v[112:127]
	v_cvt_pk_bf16_f32 v69, v211, v213
	v_cvt_pk_bf16_f32 v70, v215, v217
	v_cvt_pk_bf16_f32 v71, v219, v221
	v_cvt_pk_bf16_f32 v72, v178, v180
	v_cvt_pk_bf16_f32 v76, v179, v181
	v_pk_add_f32 v[178:179], v[178:179], v[180:181]
	v_cvt_pk_bf16_f32 v73, v222, v224
	s_waitcnt lgkmcnt(6)
	v_mfma_f32_32x32x16_bf16 v[16:31], v[48:51], v[64:67], v[16:31]
	v_add_f32_e64 v48, v194, v196
	v_add_f32_e64 v49, v195, v197
	v_add_f32_e64 v50, v214, v216
	v_add_f32_e64 v51, v215, v217
	v_add_f32_e64 v194, v218, v220
	v_add_f32_e64 v195, v219, v221
	v_pk_add_f32 v[48:49], v[48:49], 0 op_sel_hi:[1,0]
	v_pk_add_f32 v[50:51], v[50:51], v[194:195]
	v_cvt_pk_bf16_f32 v74, v226, v228
	v_pk_add_f32 v[50:51], v[50:51], 0 op_sel_hi:[1,0]
	s_waitcnt lgkmcnt(4)
	v_mfma_f32_32x32x16_bf16 v[0:15], v[52:55], v[64:67], v[0:15]
	v_add_f32_e64 v52, v222, v224
	v_add_f32_e64 v53, v223, v225
	v_add_f32_e64 v54, v226, v228
	v_add_f32_e64 v55, v227, v229
	v_add_f32_e64 v64, v182, v184
	v_add_f32_e64 v65, v183, v185
	v_pk_add_f32 v[52:53], v[178:179], v[52:53]
	v_pk_add_f32 v[54:55], v[54:55], v[64:65]
	v_pk_add_f32 v[48:49], v[48:49], v[52:53]
	v_pk_add_f32 v[50:51], v[50:51], v[54:55]
	v_mfma_f32_32x32x16_bf16 v[112:127], v[202:205], v[150:153], v[112:127]
	v_max_f32_e32 v53, v100, v100
	v_max_f32_e32 v54, v99, v99
	v_add_f32_e64 v48, v48, v50
	v_add_f32_e64 v49, v49, v51
	v_max3_f32 v52, v96, v97, v98
	v_max_f32_e32 v53, v54, v53
	v_add_f32_e32 v64, v48, v49
	ds_read_b64_tr_b16 v[48:49], v175 offset:24576
	ds_read_b64_tr_b16 v[50:51], v175 offset:26112
	s_waitcnt lgkmcnt(4)
	v_mfma_f32_32x32x16_bf16 v[16:31], v[56:59], v[68:71], v[16:31]
	v_max3_f32 v58, v52, v102, v103
	v_max3_f32 v59, v53, v101, v104
	ds_read_b64_tr_b16 v[54:55], v175 offset:26176
	ds_read_b64_tr_b16 v[52:53], v175 offset:24640
	v_cvt_pk_bf16_f32 v75, v182, v184
	v_max3_f32 v56, v112, v113, v114
	v_max3_f32 v57, v115, v116, v117
	v_cvt_pk_bf16_f32 v77, v223, v225
	s_waitcnt lgkmcnt(4)
	v_mfma_f32_32x32x16_bf16 v[0:15], v[60:63], v[68:71], v[0:15]
	v_cvt_pk_bf16_f32 v78, v227, v229
	v_cvt_pk_bf16_f32 v79, v183, v185
	s_waitcnt lgkmcnt(2)
	v_mfma_f32_32x32x16_bf16 v[16:31], v[48:51], v[72:75], v[16:31]
	v_max3_f32 v48, v56, v118, v119
	v_max3_f32 v49, v57, v120, v121
	v_max3_f32 v50, v58, v106, v107
	v_max3_f32 v51, v59, v105, v108
	v_max3_f32 v48, v48, v122, v123
	v_max3_f32 v49, v49, v124, v125
	v_max3_f32 v50, v50, v110, v111
	s_waitcnt lgkmcnt(0)
	v_mfma_f32_32x32x16_bf16 v[0:15], v[52:55], v[72:75], v[0:15]
	v_max3_f32 v48, v48, v126, v127
	v_max3_f32 v49, v51, v109, v49
	ds_read_b64_tr_b16 v[56:57], v175 offset:27648
	ds_read_b64_tr_b16 v[58:59], v175 offset:29184
	v_max3_f32 v48, v50, v48, v49
	ds_read_b64_tr_b16 v[52:53], v175 offset:29248
	ds_read_b64_tr_b16 v[50:51], v175 offset:27712
	v_mov_b32_e32 v49, v48
	v_cndmask_b32_e64 v54, 0, 1, s[2:3]
	s_waitcnt lgkmcnt(2)
	v_mfma_f32_32x32x16_bf16 v[16:31], v[56:59], v[76:79], v[16:31]
	v_permlane32_swap_b32_e32 v48, v49
	v_add_f32_e32 v176, v176, v64
	v_cmp_ne_u32_e64 s[4:5], 1, v54
	s_waitcnt lgkmcnt(0)
	v_mfma_f32_32x32x16_bf16 v[0:15], v[50:53], v[76:79], v[0:15]
	s_andn2_b64 vcc, exec, s[2:3]
	s_cbranch_vccnz .LBB0_519
	v_max_f32_e32 v48, v48, v48
	v_max_f32_e32 v49, v49, v49
	v_max_f32_e32 v48, v48, v49
	v_cmp_lt_f32_e32 vcc, s45, v48
	s_cbranch_vccnz .LBB0_533

.LBB0_527:
	ds_read_b128 v[64:67], v165
	ds_read_b128 v[68:71], v165 offset:32
	ds_read_b128 v[72:75], v165 offset:4608
	ds_read_b128 v[76:79], v165 offset:4640
	v_exp_f32_e32 v194, v96
	s_waitcnt lgkmcnt(3)
	v_mfma_f32_32x32x16_bf16 v[48:63], v[64:67], v[130:133], v[32:47]
	ds_read_b128 v[64:67], v165 offset:64
	ds_read_b128 v[160:163], v165 offset:96
	ds_read_b128 v[178:181], v165 offset:4672
	ds_read_b128 v[182:185], v165 offset:4704
	v_exp_f32_e32 v196, v97
	v_exp_f32_e32 v198, v98
	v_exp_f32_e32 v200, v99
	v_exp_f32_e32 v202, v100
	v_exp_f32_e32 v204, v101
	v_exp_f32_e32 v206, v102
	s_waitcnt lgkmcnt(5)
	v_mfma_f32_32x32x16_bf16 v[80:95], v[72:75], v[130:133], v[32:47]
	v_exp_f32_e32 v208, v103
	v_exp_f32_e32 v195, v104
	v_exp_f32_e32 v197, v105
	v_exp_f32_e32 v199, v106
	v_exp_f32_e32 v201, v107
	v_exp_f32_e32 v203, v108
	v_exp_f32_e32 v205, v109
	s_waitcnt lgkmcnt(4)
	v_mfma_f32_32x32x16_bf16 v[80:95], v[76:79], v[134:137], v[80:95]
	v_exp_f32_e32 v207, v110
	v_exp_f32_e32 v209, v111
	ds_read_b64_tr_b16 v[96:97], v175 offset:30720
	ds_read_b64_tr_b16 v[98:99], v175 offset:32256
	ds_read_b64_tr_b16 v[102:103], v175 offset:32320
	ds_read_b64_tr_b16 v[100:101], v175 offset:30784
	ds_read_b64_tr_b16 v[104:105], v175 offset:33792
	ds_read_b64_tr_b16 v[106:107], v175 offset:35328
	ds_read_b64_tr_b16 v[110:111], v175 offset:35392
	ds_read_b64_tr_b16 v[108:109], v175 offset:33856
	v_exp_f32_e32 v112, v112
	v_exp_f32_e32 v210, v113
	v_exp_f32_e32 v114, v114
	v_exp_f32_e32 v212, v115
	v_mfma_f32_32x32x16_bf16 v[48:63], v[68:71], v[134:137], v[48:63]
	v_exp_f32_e32 v113, v120
	v_exp_f32_e32 v211, v121
	v_exp_f32_e32 v115, v122
	v_exp_f32_e32 v213, v123
	v_exp_f32_e32 v116, v116
	v_exp_f32_e32 v214, v117
	v_exp_f32_e32 v118, v118
	s_waitcnt lgkmcnt(9)
	v_mfma_f32_32x32x16_bf16 v[80:95], v[178:181], v[138:141], v[80:95]
	v_exp_f32_e32 v216, v119
	v_exp_f32_e32 v117, v124
	v_exp_f32_e32 v215, v125
	v_exp_f32_e32 v119, v126
	v_exp_f32_e32 v217, v127
	v_pk_add_f32 v[120:121], v[206:207], v[208:209]
	s_and_b64 vcc, exec, s[2:3]
	v_mfma_f32_32x32x16_bf16 v[48:63], v[64:67], v[138:141], v[48:63]
	s_nop 3
	v_mov_b64_e32 v[64:65], v[80:81]
	v_mov_b64_e32 v[66:67], v[82:83]
	v_mov_b64_e32 v[68:69], v[84:85]
	v_mov_b64_e32 v[70:71], v[86:87]
	v_mov_b64_e32 v[72:73], v[88:89]
	v_mov_b64_e32 v[74:75], v[90:91]
	v_mov_b64_e32 v[76:77], v[92:93]
	v_mov_b64_e32 v[78:79], v[94:95]
	v_cvt_pk_bf16_f32 v80, v194, v196
	v_cvt_pk_bf16_f32 v81, v198, v200
	v_cvt_pk_bf16_f32 v82, v202, v204
	v_cvt_pk_bf16_f32 v83, v206, v208
	v_mfma_f32_32x32x16_bf16 v[48:63], v[160:163], v[150:153], v[48:63]
	v_cvt_pk_bf16_f32 v84, v195, v197
	v_cvt_pk_bf16_f32 v85, v199, v201
	v_cvt_pk_bf16_f32 v86, v203, v205
	v_cvt_pk_bf16_f32 v87, v207, v209
	v_cvt_pk_bf16_f32 v88, v112, v210
	v_cvt_pk_bf16_f32 v89, v114, v212
	v_cvt_pk_bf16_f32 v90, v116, v214
	s_waitcnt lgkmcnt(6)
	v_mfma_f32_32x32x16_bf16 v[16:31], v[96:99], v[80:83], v[16:31]
	v_add_f32_e64 v96, v194, v196
	v_add_f32_e64 v97, v195, v197
	v_add_f32_e64 v98, v198, v200
	v_add_f32_e64 v99, v199, v201
	v_cvt_pk_bf16_f32 v91, v118, v216
	v_pk_add_f32 v[96:97], v[96:97], v[98:99]
	v_pk_add_f32 v[98:99], v[202:203], v[204:205]
	v_pk_add_f32 v[96:97], v[96:97], 0 op_sel_hi:[1,0]
	v_pk_add_f32 v[98:99], v[98:99], v[120:121]
	s_waitcnt lgkmcnt(4)
	v_mfma_f32_32x32x16_bf16 v[0:15], v[100:103], v[80:83], v[0:15]
	v_add_f32_e64 v80, v98, 0
	v_add_f32_e64 v81, v99, 0
	v_add_f32_e64 v82, v112, v210
	v_add_f32_e64 v83, v113, v211
	v_add_f32_e64 v98, v114, v212
	v_add_f32_e64 v99, v115, v213
	v_pk_add_f32 v[100:101], v[118:119], v[216:217]
	v_pk_add_f32 v[82:83], v[82:83], v[98:99]
	v_pk_add_f32 v[98:99], v[116:117], v[214:215]
	v_pk_add_f32 v[82:83], v[82:83], v[96:97]
	v_mfma_f32_32x32x16_bf16 v[64:79], v[182:185], v[150:153], v[64:79]
	v_add_f32_e64 v98, v98, v100
	v_add_f32_e64 v99, v99, v101
	v_max3_f32 v97, v48, v49, v50
	v_add_f32_e64 v80, v98, v80
	v_add_f32_e64 v81, v99, v81
	v_cvt_pk_bf16_f32 v92, v113, v211
	v_pk_add_f32 v[80:81], v[82:83], v[80:81]
	v_cvt_pk_bf16_f32 v93, v115, v213
	v_add_f32_e32 v96, v80, v81
	s_waitcnt lgkmcnt(2)
	v_mfma_f32_32x32x16_bf16 v[16:31], v[104:107], v[84:87], v[16:31]
	ds_read_b64_tr_b16 v[80:81], v175 offset:36864
	ds_read_b64_tr_b16 v[82:83], v175 offset:38400
	v_max3_f32 v99, v64, v65, v66
	v_max3_f32 v100, v67, v68, v69
	v_cvt_pk_bf16_f32 v94, v117, v215
	v_cvt_pk_bf16_f32 v95, v119, v217
	v_add_f32_e32 v176, v176, v96
	s_waitcnt lgkmcnt(2)
	v_mfma_f32_32x32x16_bf16 v[0:15], v[108:111], v[84:87], v[0:15]
	v_max_f32_e32 v84, v52, v52
	v_max_f32_e32 v85, v51, v51
	v_max_f32_e32 v98, v85, v84
	ds_read_b64_tr_b16 v[86:87], v175 offset:38464
	ds_read_b64_tr_b16 v[84:85], v175 offset:36928
	s_waitcnt lgkmcnt(2)
	v_mfma_f32_32x32x16_bf16 v[16:31], v[80:83], v[88:91], v[16:31]
	v_max3_f32 v80, v97, v54, v55
	v_max3_f32 v97, v98, v53, v56
	v_max3_f32 v98, v99, v70, v71
	v_max3_f32 v99, v100, v72, v73
	v_max3_f32 v100, v80, v58, v59
	ds_read_b64_tr_b16 v[80:81], v175 offset:39936
	ds_read_b64_tr_b16 v[82:83], v175 offset:41472
	s_waitcnt lgkmcnt(2)
	v_mfma_f32_32x32x16_bf16 v[0:15], v[84:87], v[88:91], v[0:15]
	v_max3_f32 v84, v98, v74, v75
	v_max3_f32 v91, v84, v78, v79
	ds_read_b64_tr_b16 v[86:87], v175 offset:41536
	ds_read_b64_tr_b16 v[84:85], v175 offset:40000
	v_max3_f32 v88, v97, v57, v60
	v_max3_f32 v89, v99, v76, v77
	v_max3_f32 v90, v100, v62, v63
	s_waitcnt lgkmcnt(2)
	v_mfma_f32_32x32x16_bf16 v[16:31], v[80:83], v[92:95], v[16:31]
	v_max3_f32 v80, v88, v61, v89
	v_max3_f32 v80, v90, v91, v80
	v_mov_b32_e32 v81, v80
	s_nop 1
	v_permlane32_swap_b32_e32 v80, v81
	s_waitcnt lgkmcnt(0)
	v_mfma_f32_32x32x16_bf16 v[0:15], v[84:87], v[92:95], v[0:15]
	s_cbranch_vccnz .LBB0_529
	v_max_f32_e32 v80, v80, v80
	v_max_f32_e32 v81, v81, v81
	v_max_f32_e32 v80, v80, v81
	v_cmp_lt_f32_e32 vcc, s45, v80
	s_cbranch_vccnz .LBB0_534

.LBB0_617:
	ds_read_b128 v[80:83], v202 offset:13312
	ds_read_b128 v[84:87], v202 offset:13344
	s_waitcnt lgkmcnt(1)
	v_mfma_f32_32x32x16_bf16 v[96:111], v[80:83], v[144:147], v[32:47]
	ds_read_b128 v[80:83], v202 offset:19968
	ds_read_b128 v[206:209], v202 offset:20000
	v_exp_f32_e32 v218, v48
	s_waitcnt lgkmcnt(2)
	v_mfma_f32_32x32x16_bf16 v[96:111], v[84:87], v[148:151], v[96:111]
	v_exp_f32_e32 v220, v49
	v_exp_f32_e32 v222, v50
	v_exp_f32_e32 v224, v51
	v_exp_f32_e32 v226, v52
	v_exp_f32_e32 v228, v53
	v_exp_f32_e32 v230, v54
	v_exp_f32_e32 v232, v55
	s_waitcnt lgkmcnt(1)
	v_mfma_f32_32x32x16_bf16 v[112:127], v[80:83], v[144:147], v[32:47]
	ds_read_b128 v[80:83], v202 offset:13376
	ds_read_b128 v[210:213], v202 offset:13408
	ds_read_b128 v[214:217], v202 offset:20032
	ds_read_b128 v[48:51], v202 offset:20064
	v_exp_f32_e32 v219, v56
	v_exp_f32_e32 v221, v57
	v_exp_f32_e32 v223, v58
	v_exp_f32_e32 v225, v59
	s_waitcnt lgkmcnt(4)
	v_mfma_f32_32x32x16_bf16 v[112:127], v[206:209], v[148:151], v[112:127]
	ds_read_b128 v[52:55], v202 offset:13440
	ds_read_b128 v[56:59], v202 offset:13472
	v_exp_f32_e32 v227, v60
	v_exp_f32_e32 v229, v61
	v_exp_f32_e32 v231, v62
	v_exp_f32_e32 v233, v63
	ds_read_b128 v[60:63], v202 offset:20096
	ds_read_b128 v[206:209], v202 offset:20128
	v_exp_f32_e32 v234, v68
	s_waitcnt lgkmcnt(7)
	v_mfma_f32_32x32x16_bf16 v[96:111], v[80:83], v[152:155], v[96:111]
	v_exp_f32_e32 v236, v69
	v_exp_f32_e32 v238, v70
	v_exp_f32_e32 v240, v71
	v_cvt_pk_bf16_f32 v68, v218, v220
	v_cvt_pk_bf16_f32 v69, v222, v224
	v_cvt_pk_bf16_f32 v70, v226, v228
	v_cvt_pk_bf16_f32 v71, v230, v232
	s_waitcnt lgkmcnt(5)
	v_mfma_f32_32x32x16_bf16 v[112:127], v[214:217], v[152:155], v[112:127]
	v_exp_f32_e32 v214, v66
	v_exp_f32_e32 v216, v67
	v_exp_f32_e32 v215, v74
	v_exp_f32_e32 v217, v75
	v_exp_f32_e32 v235, v76
	v_exp_f32_e32 v237, v77
	v_exp_f32_e32 v239, v78
	v_mfma_f32_32x32x16_bf16 v[96:111], v[210:213], v[156:159], v[96:111]
	v_exp_f32_e32 v210, v64
	v_exp_f32_e32 v212, v65
	v_exp_f32_e32 v211, v72
	v_exp_f32_e32 v213, v73
	v_exp_f32_e32 v241, v79
	v_cvt_pk_bf16_f32 v72, v210, v212
	v_cvt_pk_bf16_f32 v73, v214, v216
	s_waitcnt lgkmcnt(4)
	v_mfma_f32_32x32x16_bf16 v[112:127], v[48:51], v[156:159], v[112:127]
	v_cvt_pk_bf16_f32 v74, v234, v236
	v_cvt_pk_bf16_f32 v75, v238, v240
	v_cvt_pk_bf16_f32 v76, v211, v213
	v_cvt_pk_bf16_f32 v77, v215, v217
	v_cvt_pk_bf16_f32 v78, v235, v237
	v_cvt_pk_bf16_f32 v79, v239, v241
	s_waitcnt lgkmcnt(3)
	v_mfma_f32_32x32x16_bf16 v[96:111], v[52:55], v[160:163], v[96:111]
	ds_read_b64_tr_b16 v[48:49], v175 offset:26624
	ds_read_b64_tr_b16 v[50:51], v175 offset:28160
	ds_read_b64_tr_b16 v[54:55], v175 offset:28224
	ds_read_b64_tr_b16 v[52:53], v175 offset:26688
	s_waitcnt lgkmcnt(5)
	v_mfma_f32_32x32x16_bf16 v[112:127], v[60:63], v[160:163], v[112:127]
	ds_read_b64_tr_b16 v[60:61], v175 offset:29696
	ds_read_b64_tr_b16 v[62:63], v175 offset:31232
	ds_read_b64_tr_b16 v[66:67], v175 offset:31296
	ds_read_b64_tr_b16 v[64:65], v175 offset:29760
	s_andn2_b64 vcc, exec, s[8:9]
	s_waitcnt lgkmcnt(6)
	v_mfma_f32_32x32x16_bf16 v[16:31], v[48:51], v[68:71], v[16:31]
	v_add_f32_e64 v50, v226, v228
	v_add_f32_e64 v51, v227, v229
	s_waitcnt lgkmcnt(4)
	v_mfma_f32_32x32x16_bf16 v[0:15], v[52:55], v[68:71], v[0:15]
	v_add_f32_e64 v52, v214, v216
	v_add_f32_e64 v53, v215, v217
	v_add_f32_e64 v54, v234, v236
	v_add_f32_e64 v55, v235, v237
	v_add_f32_e64 v68, v238, v240
	v_add_f32_e64 v69, v239, v241
	v_pk_add_f32 v[54:55], v[54:55], v[68:69]
	v_mfma_f32_32x32x16_bf16 v[96:111], v[56:59], v[164:167], v[96:111]
	v_cvt_pk_bf16_f32 v56, v219, v221
	v_cvt_pk_bf16_f32 v57, v223, v225
	v_cvt_pk_bf16_f32 v58, v227, v229
	v_cvt_pk_bf16_f32 v59, v231, v233
	v_mfma_f32_32x32x16_bf16 v[112:127], v[206:209], v[164:167], v[112:127]
	v_add_f32_e64 v206, v218, v220
	v_add_f32_e64 v207, v219, v221
	v_add_f32_e64 v208, v222, v224
	v_add_f32_e64 v209, v223, v225
	v_add_f32_e64 v48, v206, v208
	v_add_f32_e64 v49, v207, v209
	v_pk_add_f32 v[206:207], v[230:231], v[232:233]
	v_pk_add_f32 v[48:49], v[48:49], 0 op_sel_hi:[1,0]
	v_pk_add_f32 v[50:51], v[50:51], v[206:207]
	v_pk_add_f32 v[206:207], v[210:211], v[212:213]
	v_pk_add_f32 v[50:51], v[50:51], 0 op_sel_hi:[1,0]
	v_pk_add_f32 v[52:53], v[206:207], v[52:53]
	s_waitcnt lgkmcnt(2)
	v_mfma_f32_32x32x16_bf16 v[16:31], v[60:63], v[56:59], v[16:31]
	v_add_f32_e64 v48, v48, v52
	v_add_f32_e64 v49, v49, v53
	v_add_f32_e64 v50, v50, v54
	v_add_f32_e64 v51, v51, v55
	v_max_f32_e32 v53, v100, v100
	v_max_f32_e32 v54, v99, v99
	v_pk_add_f32 v[48:49], v[48:49], v[50:51]
	v_max3_f32 v52, v96, v97, v98
	v_max_f32_e32 v53, v54, v53
	s_waitcnt lgkmcnt(0)
	v_mfma_f32_32x32x16_bf16 v[0:15], v[64:67], v[56:59], v[0:15]
	v_add_f32_e32 v60, v48, v49
	ds_read_b64_tr_b16 v[48:49], v175 offset:32768
	ds_read_b64_tr_b16 v[50:51], v175 offset:34304
	v_max3_f32 v58, v52, v102, v103
	v_max3_f32 v59, v53, v101, v104
	ds_read_b64_tr_b16 v[54:55], v175 offset:34368
	ds_read_b64_tr_b16 v[52:53], v175 offset:32832
	v_max3_f32 v56, v112, v113, v114
	v_max3_f32 v57, v115, v116, v117
	s_waitcnt lgkmcnt(2)
	v_mfma_f32_32x32x16_bf16 v[16:31], v[48:51], v[72:75], v[16:31]
	v_max3_f32 v48, v56, v118, v119
	v_max3_f32 v49, v57, v120, v121
	v_max3_f32 v50, v58, v106, v107
	v_max3_f32 v51, v59, v105, v108
	v_max3_f32 v48, v48, v122, v123
	v_max3_f32 v49, v49, v124, v125
	v_max3_f32 v50, v50, v110, v111
	s_waitcnt lgkmcnt(0)
	v_mfma_f32_32x32x16_bf16 v[0:15], v[52:55], v[72:75], v[0:15]
	v_max3_f32 v48, v48, v126, v127
	v_max3_f32 v49, v51, v109, v49
	ds_read_b64_tr_b16 v[56:57], v175 offset:35840
	ds_read_b64_tr_b16 v[58:59], v175 offset:37376
	v_max3_f32 v48, v50, v48, v49
	ds_read_b64_tr_b16 v[52:53], v175 offset:37440
	ds_read_b64_tr_b16 v[50:51], v175 offset:35904
	v_mov_b32_e32 v49, v48
	v_cndmask_b32_e64 v54, 0, 1, s[8:9]
	s_waitcnt lgkmcnt(2)
	v_mfma_f32_32x32x16_bf16 v[16:31], v[56:59], v[76:79], v[16:31]
	v_permlane32_swap_b32_e32 v48, v49
	v_add_f32_e32 v205, v205, v60
	v_cmp_ne_u32_e64 s[10:11], 1, v54
	s_waitcnt lgkmcnt(0)
	v_mfma_f32_32x32x16_bf16 v[0:15], v[50:53], v[76:79], v[0:15]
	s_cbranch_vccnz .LBB0_619
	v_max_f32_e32 v48, v48, v48
	v_max_f32_e32 v49, v49, v49
	v_max_f32_e32 v48, v48, v49
	v_cmp_lt_f32_e32 vcc, s45, v48
	s_cbranch_vccnz .LBB0_649

.LBB0_639:
	ds_read_b128 v[64:67], v202
	ds_read_b128 v[68:71], v202 offset:32
	v_exp_f32_e32 v184, v96
	v_exp_f32_e32 v206, v97
	v_exp_f32_e32 v208, v98
	s_waitcnt lgkmcnt(1)
	v_mfma_f32_32x32x16_bf16 v[48:63], v[64:67], v[144:147], v[32:47]
	v_exp_f32_e32 v210, v99
	v_exp_f32_e32 v212, v100
	v_exp_f32_e32 v214, v101
	v_exp_f32_e32 v216, v102
	v_exp_f32_e32 v218, v103
	v_exp_f32_e32 v185, v104
	v_exp_f32_e32 v207, v105
	s_waitcnt lgkmcnt(0)
	v_mfma_f32_32x32x16_bf16 v[48:63], v[68:71], v[148:151], v[48:63]
	ds_read_b128 v[64:67], v202 offset:6656
	ds_read_b128 v[68:71], v202 offset:6688
	v_exp_f32_e32 v209, v106
	v_exp_f32_e32 v211, v107
	v_exp_f32_e32 v213, v108
	v_exp_f32_e32 v215, v109
	v_exp_f32_e32 v217, v110
	v_exp_f32_e32 v219, v111
	s_waitcnt lgkmcnt(1)
	v_mfma_f32_32x32x16_bf16 v[80:95], v[64:67], v[144:147], v[32:47]
	ds_read_b128 v[64:67], v202 offset:64
	ds_read_b128 v[72:75], v202 offset:96
	v_exp_f32_e32 v220, v112
	v_exp_f32_e32 v222, v113
	v_exp_f32_e32 v224, v114
	v_exp_f32_e32 v226, v115
	v_exp_f32_e32 v228, v116
	v_exp_f32_e32 v230, v117
	s_waitcnt lgkmcnt(1)
	v_mfma_f32_32x32x16_bf16 v[48:63], v[64:67], v[152:155], v[48:63]
	ds_read_b128 v[64:67], v202 offset:6720
	v_exp_f32_e32 v232, v118
	v_exp_f32_e32 v234, v119
	v_exp_f32_e32 v221, v120
	v_exp_f32_e32 v223, v121
	v_exp_f32_e32 v225, v122
	v_exp_f32_e32 v227, v123
	v_mfma_f32_32x32x16_bf16 v[80:95], v[68:71], v[148:151], v[80:95]
	ds_read_b128 v[68:71], v202 offset:6752
	v_exp_f32_e32 v229, v124
	v_exp_f32_e32 v231, v125
	v_exp_f32_e32 v233, v126
	v_exp_f32_e32 v235, v127
	s_and_b64 vcc, exec, s[8:9]
	s_waitcnt lgkmcnt(1)
	v_mfma_f32_32x32x16_bf16 v[80:95], v[64:67], v[152:155], v[80:95]
	s_waitcnt lgkmcnt(0)
	v_mfma_f32_32x32x16_bf16 v[80:95], v[68:71], v[156:159], v[80:95]
	v_mfma_f32_32x32x16_bf16 v[48:63], v[72:75], v[156:159], v[48:63]
	ds_read_b128 v[64:67], v202 offset:128
	ds_read_b128 v[96:99], v202 offset:160
	ds_read_b128 v[72:75], v202 offset:6784
	ds_read_b128 v[100:103], v202 offset:6816
	ds_read_b64_tr_b16 v[104:105], v175 offset:38912
	ds_read_b64_tr_b16 v[106:107], v175 offset:40448
	ds_read_b64_tr_b16 v[110:111], v175 offset:40512
	ds_read_b64_tr_b16 v[108:109], v175 offset:38976
	ds_read_b64_tr_b16 v[112:113], v175 offset:41984
	ds_read_b64_tr_b16 v[114:115], v175 offset:43520
	ds_read_b64_tr_b16 v[118:119], v175 offset:43584
	ds_read_b64_tr_b16 v[116:117], v175 offset:42048
	s_waitcnt lgkmcnt(9)
	v_mfma_f32_32x32x16_bf16 v[80:95], v[72:75], v[160:163], v[80:95]
	v_mfma_f32_32x32x16_bf16 v[48:63], v[64:67], v[160:163], v[48:63]
	s_nop 10
	v_mov_b64_e32 v[64:65], v[80:81]
	v_mov_b64_e32 v[66:67], v[82:83]
	v_mov_b64_e32 v[68:69], v[84:85]
	v_mov_b64_e32 v[70:71], v[86:87]
	v_mov_b64_e32 v[72:73], v[88:89]
	v_mov_b64_e32 v[74:75], v[90:91]
	v_mov_b64_e32 v[76:77], v[92:93]
	v_mov_b64_e32 v[78:79], v[94:95]
	v_cvt_pk_bf16_f32 v80, v184, v206
	v_cvt_pk_bf16_f32 v81, v208, v210
	v_cvt_pk_bf16_f32 v82, v212, v214
	v_cvt_pk_bf16_f32 v83, v216, v218
	v_mfma_f32_32x32x16_bf16 v[48:63], v[96:99], v[164:167], v[48:63]
	v_add_f32_e64 v96, v184, v206
	v_add_f32_e64 v97, v185, v207
	v_add_f32_e64 v98, v208, v210
	v_add_f32_e64 v99, v209, v211
	v_cvt_pk_bf16_f32 v84, v185, v207
	v_pk_add_f32 v[96:97], v[96:97], v[98:99]
	v_pk_add_f32 v[98:99], v[212:213], v[214:215]
	v_cvt_pk_bf16_f32 v85, v209, v211
	v_cvt_pk_bf16_f32 v86, v213, v215
	s_waitcnt lgkmcnt(6)
	v_mfma_f32_32x32x16_bf16 v[16:31], v[104:107], v[80:83], v[16:31]
	v_cvt_pk_bf16_f32 v87, v217, v219
	v_add_f32_e64 v96, v96, 0
	v_add_f32_e64 v97, v97, 0
	v_cvt_pk_bf16_f32 v88, v220, v222
	v_cvt_pk_bf16_f32 v89, v224, v226
	v_cvt_pk_bf16_f32 v90, v228, v230
	v_cvt_pk_bf16_f32 v91, v232, v234
	v_cvt_pk_bf16_f32 v92, v221, v223
	s_waitcnt lgkmcnt(4)
	v_mfma_f32_32x32x16_bf16 v[0:15], v[108:111], v[80:83], v[0:15]
	v_add_f32_e64 v82, v220, v222
	v_add_f32_e64 v83, v221, v223
	v_cvt_pk_bf16_f32 v93, v225, v227
	v_cvt_pk_bf16_f32 v94, v229, v231
	v_cvt_pk_bf16_f32 v95, v233, v235
	v_mfma_f32_32x32x16_bf16 v[64:79], v[100:103], v[164:167], v[64:79]
	v_add_f32_e64 v100, v216, v218
	v_add_f32_e64 v101, v217, v219
	v_add_f32_e64 v98, v98, v100
	v_add_f32_e64 v99, v99, v101
	v_add_f32_e64 v100, v232, v234
	v_add_f32_e64 v101, v233, v235
	v_pk_add_f32 v[80:81], v[98:99], 0 op_sel_hi:[1,0]
	v_pk_add_f32 v[98:99], v[224:225], v[226:227]
	s_nop 0
	v_pk_add_f32 v[82:83], v[82:83], v[98:99]
	v_pk_add_f32 v[98:99], v[228:229], v[230:231]
	s_waitcnt lgkmcnt(2)
	v_mfma_f32_32x32x16_bf16 v[16:31], v[112:115], v[84:87], v[16:31]
	v_add_f32_e64 v98, v98, v100
	v_add_f32_e64 v99, v99, v101
	v_add_f32_e64 v82, v82, v96
	v_add_f32_e64 v83, v83, v97
	v_add_f32_e64 v80, v98, v80
	v_add_f32_e64 v81, v99, v81
	v_max3_f32 v97, v48, v49, v50
	v_pk_add_f32 v[80:81], v[82:83], v[80:81]
	v_max3_f32 v99, v64, v65, v66
	v_add_f32_e32 v96, v80, v81
	s_waitcnt lgkmcnt(0)
	v_mfma_f32_32x32x16_bf16 v[0:15], v[116:119], v[84:87], v[0:15]
	v_max_f32_e32 v84, v52, v52
	v_max_f32_e32 v85, v51, v51
	ds_read_b64_tr_b16 v[80:81], v175 offset:45056
	ds_read_b64_tr_b16 v[82:83], v175 offset:46592
	v_max_f32_e32 v98, v85, v84
	ds_read_b64_tr_b16 v[86:87], v175 offset:46656
	ds_read_b64_tr_b16 v[84:85], v175 offset:45120
	v_max3_f32 v100, v67, v68, v69
	v_add_f32_e32 v205, v205, v96
	s_waitcnt lgkmcnt(2)
	v_mfma_f32_32x32x16_bf16 v[16:31], v[80:83], v[88:91], v[16:31]
	v_max3_f32 v80, v97, v54, v55
	v_max3_f32 v97, v98, v53, v56
	v_max3_f32 v98, v99, v70, v71
	v_max3_f32 v99, v100, v72, v73
	v_max3_f32 v100, v80, v58, v59
	ds_read_b64_tr_b16 v[80:81], v175 offset:48128
	ds_read_b64_tr_b16 v[82:83], v175 offset:49664
	s_waitcnt lgkmcnt(2)
	v_mfma_f32_32x32x16_bf16 v[0:15], v[84:87], v[88:91], v[0:15]
	v_max3_f32 v84, v98, v74, v75
	v_max3_f32 v91, v84, v78, v79
	ds_read_b64_tr_b16 v[86:87], v175 offset:49728
	ds_read_b64_tr_b16 v[84:85], v175 offset:48192
	v_max3_f32 v88, v97, v57, v60
	v_max3_f32 v89, v99, v76, v77
	v_max3_f32 v90, v100, v62, v63
	s_waitcnt lgkmcnt(2)
	v_mfma_f32_32x32x16_bf16 v[16:31], v[80:83], v[92:95], v[16:31]
	v_max3_f32 v80, v88, v61, v89
	v_max3_f32 v80, v90, v91, v80
	v_mov_b32_e32 v81, v80
	s_nop 1
	v_permlane32_swap_b32_e32 v80, v81
	s_waitcnt lgkmcnt(0)
	v_mfma_f32_32x32x16_bf16 v[0:15], v[84:87], v[92:95], v[0:15]
	s_cbranch_vccnz .LBB0_641
	v_max_f32_e32 v80, v80, v80
	v_max_f32_e32 v81, v81, v81
	v_max_f32_e32 v80, v80, v81
	v_cmp_lt_f32_e32 vcc, s45, v80
	s_cbranch_vccnz .LBB0_650

.LBB0_1757:
	ds_read_b128 v[112:115], v165 offset:9216
	ds_read_b128 v[116:119], v165 offset:9248
	v_lshl_add_u64 v[162:163], v[158:159], 0, s[8:9]
	v_exp_f32_e32 v208, v48
	v_add_co_u32_e32 v48, vcc, 0x6d90000, v162
	v_exp_f32_e32 v210, v49
	s_nop 0
	v_addc_co_u32_e32 v49, vcc, 0, v163, vcc
	s_waitcnt lgkmcnt(1)
	v_mfma_f32_32x32x16_bf16 v[96:111], v[112:115], v[130:133], v[32:47]
	ds_read_b128 v[178:181], v165 offset:13824
	ds_read_b128 v[182:185], v165 offset:13856
	ds_read_b128 v[112:115], v165 offset:9280
	ds_read_b128 v[196:199], v165 offset:9312
	ds_read_b128 v[200:203], v165 offset:13888
	ds_read_b128 v[204:207], v165 offset:13920
	global_load_dwordx4 v[150:153], v[48:49], off offset:2112
	v_exp_f32_e32 v212, v50
	v_exp_f32_e32 v214, v51
	v_exp_f32_e32 v216, v52
	v_exp_f32_e32 v218, v53
	v_exp_f32_e32 v220, v54
	s_waitcnt lgkmcnt(6)
	v_mfma_f32_32x32x16_bf16 v[96:111], v[116:119], v[134:137], v[96:111]
	v_exp_f32_e32 v222, v55
	v_exp_f32_e32 v209, v56
	v_exp_f32_e32 v211, v57
	v_exp_f32_e32 v213, v58
	v_exp_f32_e32 v215, v59
	v_exp_f32_e32 v217, v60
	v_exp_f32_e32 v219, v61
	s_waitcnt lgkmcnt(3)
	v_mfma_f32_32x32x16_bf16 v[96:111], v[112:115], v[138:141], v[96:111]
	v_exp_f32_e32 v221, v62
	v_exp_f32_e32 v223, v63
	v_mfma_f32_32x32x16_bf16 v[112:127], v[178:181], v[130:133], v[32:47]
	v_exp_f32_e32 v178, v64
	v_exp_f32_e32 v180, v65
	ds_read_b64_tr_b16 v[48:49], v175 offset:18432
	ds_read_b64_tr_b16 v[50:51], v175 offset:19968
	ds_read_b64_tr_b16 v[54:55], v175 offset:20032
	ds_read_b64_tr_b16 v[52:53], v175 offset:18496
	ds_read_b64_tr_b16 v[56:57], v175 offset:21504
	ds_read_b64_tr_b16 v[58:59], v175 offset:23040
	ds_read_b64_tr_b16 v[62:63], v175 offset:23104
	ds_read_b64_tr_b16 v[60:61], v175 offset:21568
	v_cvt_pk_bf16_f32 v64, v208, v210
	v_cvt_pk_bf16_f32 v65, v212, v214
	v_exp_f32_e32 v179, v72
	v_exp_f32_e32 v181, v73
	v_mfma_f32_32x32x16_bf16 v[112:127], v[182:185], v[134:137], v[112:127]
	v_exp_f32_e32 v182, v66
	v_exp_f32_e32 v184, v67
	v_cvt_pk_bf16_f32 v66, v216, v218
	v_cvt_pk_bf16_f32 v67, v220, v222
	v_exp_f32_e32 v183, v74
	v_exp_f32_e32 v185, v75
	v_exp_f32_e32 v224, v68
	s_waitcnt lgkmcnt(6)
	v_mfma_f32_32x32x16_bf16 v[16:31], v[48:51], v[64:67], v[16:31]
	v_exp_f32_e32 v226, v69
	v_exp_f32_e32 v228, v70
	v_exp_f32_e32 v230, v71
	v_exp_f32_e32 v225, v76
	v_exp_f32_e32 v227, v77
	v_exp_f32_e32 v229, v78
	v_exp_f32_e32 v231, v79
	s_waitcnt lgkmcnt(4)
	v_mfma_f32_32x32x16_bf16 v[0:15], v[52:55], v[64:67], v[0:15]
	v_add_f32_e64 v48, v208, v210
	v_add_f32_e64 v49, v209, v211
	v_add_f32_e64 v50, v212, v214
	v_add_f32_e64 v51, v213, v215
	v_add_f32_e64 v52, v178, v180
	v_add_f32_e64 v53, v179, v181
	v_pk_add_f32 v[48:49], v[48:49], v[50:51]
	v_pk_add_f32 v[50:51], v[216:217], v[218:219]
	v_pk_add_f32 v[54:55], v[182:183], v[184:185]
	v_cvt_pk_bf16_f32 v68, v209, v211
	v_mfma_f32_32x32x16_bf16 v[112:127], v[200:203], v[138:141], v[112:127]
	v_cvt_pk_bf16_f32 v69, v213, v215
	v_cvt_pk_bf16_f32 v70, v217, v219
	v_cvt_pk_bf16_f32 v71, v221, v223
	v_add_f32_e64 v52, v52, v54
	v_add_f32_e64 v53, v53, v55
	v_pk_add_f32 v[54:55], v[224:225], v[226:227]
	v_pk_add_f32 v[64:65], v[228:229], v[230:231]
	v_pk_add_f32 v[48:49], v[48:49], 0 op_sel_hi:[1,0]
	v_mfma_f32_32x32x16_bf16 v[96:111], v[196:199], v[142:145], v[96:111]
	v_add_f32_e64 v196, v220, v222
	v_add_f32_e64 v197, v221, v223
	v_add_f32_e64 v54, v54, v64
	v_add_f32_e64 v55, v55, v65
	v_add_f32_e64 v50, v50, v196
	v_add_f32_e64 v51, v51, v197
	v_pk_add_f32 v[48:49], v[48:49], v[52:53]
	v_pk_add_f32 v[50:51], v[50:51], 0 op_sel_hi:[1,0]
	v_cvt_pk_bf16_f32 v72, v178, v180
	v_pk_add_f32 v[50:51], v[50:51], v[54:55]
	s_waitcnt lgkmcnt(2)
	v_mfma_f32_32x32x16_bf16 v[16:31], v[56:59], v[68:71], v[16:31]
	v_add_f32_e64 v48, v48, v50
	v_add_f32_e64 v49, v49, v51
	v_max_f32_e32 v52, v100, v100
	v_max_f32_e32 v53, v99, v99
	v_add_f32_e32 v56, v48, v49
	ds_read_b64_tr_b16 v[48:49], v175 offset:24576
	ds_read_b64_tr_b16 v[50:51], v175 offset:26112
	v_max_f32_e32 v58, v53, v52
	ds_read_b64_tr_b16 v[54:55], v175 offset:26176
	ds_read_b64_tr_b16 v[52:53], v175 offset:24640
	s_waitcnt lgkmcnt(4)
	v_mfma_f32_32x32x16_bf16 v[0:15], v[60:63], v[68:71], v[0:15]
	v_cvt_pk_bf16_f32 v73, v182, v184
	v_cvt_pk_bf16_f32 v74, v224, v226
	v_cvt_pk_bf16_f32 v75, v228, v230
	v_max3_f32 v57, v96, v97, v98
	v_max3_f32 v57, v57, v102, v103
	v_max3_f32 v58, v58, v101, v104
	v_cvt_pk_bf16_f32 v76, v179, v181
	v_mfma_f32_32x32x16_bf16 v[112:127], v[204:207], v[142:145], v[112:127]
	v_cvt_pk_bf16_f32 v77, v183, v185
	v_cvt_pk_bf16_f32 v78, v225, v227
	v_cvt_pk_bf16_f32 v79, v229, v231
	v_add_f32_e32 v176, v176, v56
	s_waitcnt lgkmcnt(2)
	v_mfma_f32_32x32x16_bf16 v[16:31], v[48:51], v[72:75], v[16:31]
	s_nop 5
	v_max3_f32 v59, v112, v113, v114
	v_max3_f32 v48, v115, v116, v117
	v_max3_f32 v59, v59, v118, v119
	v_max3_f32 v60, v48, v120, v121
	ds_read_b64_tr_b16 v[48:49], v175 offset:27648
	ds_read_b64_tr_b16 v[50:51], v175 offset:29184
	s_waitcnt lgkmcnt(2)
	v_mfma_f32_32x32x16_bf16 v[0:15], v[52:55], v[72:75], v[0:15]
	v_max3_f32 v52, v57, v106, v107
	v_max3_f32 v57, v58, v105, v108
	v_max3_f32 v58, v59, v122, v123
	v_max3_f32 v59, v60, v124, v125
	v_max3_f32 v60, v52, v110, v111
	ds_read_b64_tr_b16 v[54:55], v175 offset:29248
	ds_read_b64_tr_b16 v[52:53], v175 offset:27712
	s_waitcnt lgkmcnt(2)
	v_mfma_f32_32x32x16_bf16 v[16:31], v[48:51], v[76:79], v[16:31]
	v_max3_f32 v48, v58, v126, v127
	v_max3_f32 v49, v57, v109, v59
	v_max3_f32 v48, v60, v48, v49
	v_mov_b32_e32 v49, v48
	s_nop 1
	v_permlane32_swap_b32_e32 v48, v49
	v_max_f32_e32 v49, v49, v49
	s_waitcnt lgkmcnt(0)
	v_mfma_f32_32x32x16_bf16 v[0:15], v[52:55], v[76:79], v[0:15]
	v_max_f32_e32 v48, v48, v48
	v_max_f32_e32 v48, v48, v49
	v_cmp_lt_f32_e32 vcc, s51, v48
	s_cbranch_vccnz .LBB0_1770
	v_cndmask_b32_e64 v48, 0, 1, s[40:41]
	v_cmp_ne_u32_e64 s[2:3], 1, v48
	s_andn2_b64 vcc, exec, s[40:41]
	s_cbranch_vccnz .LBB0_1760

.LBB0_1764:
	ds_read_b128 v[64:67], v165
	ds_read_b128 v[68:71], v165 offset:32
	ds_read_b128 v[72:75], v165 offset:4608
	ds_read_b128 v[76:79], v165 offset:4640
	v_exp_f32_e32 v196, v96
	s_waitcnt lgkmcnt(3)
	v_mfma_f32_32x32x16_bf16 v[48:63], v[64:67], v[130:133], v[32:47]
	ds_read_b128 v[64:67], v165 offset:64
	ds_read_b128 v[160:163], v165 offset:96
	ds_read_b128 v[178:181], v165 offset:4672
	ds_read_b128 v[182:185], v165 offset:4704
	v_exp_f32_e32 v198, v97
	v_exp_f32_e32 v200, v98
	v_exp_f32_e32 v202, v99
	v_exp_f32_e32 v204, v100
	v_exp_f32_e32 v206, v101
	v_exp_f32_e32 v208, v102
	s_waitcnt lgkmcnt(5)
	v_mfma_f32_32x32x16_bf16 v[80:95], v[72:75], v[130:133], v[32:47]
	v_exp_f32_e32 v210, v103
	v_exp_f32_e32 v197, v104
	v_exp_f32_e32 v199, v105
	v_exp_f32_e32 v201, v106
	v_exp_f32_e32 v203, v107
	v_exp_f32_e32 v205, v108
	v_exp_f32_e32 v207, v109
	s_waitcnt lgkmcnt(4)
	v_mfma_f32_32x32x16_bf16 v[80:95], v[76:79], v[134:137], v[80:95]
	v_exp_f32_e32 v209, v110
	v_exp_f32_e32 v211, v111
	ds_read_b64_tr_b16 v[96:97], v175 offset:30720
	ds_read_b64_tr_b16 v[98:99], v175 offset:32256
	ds_read_b64_tr_b16 v[102:103], v175 offset:32320
	ds_read_b64_tr_b16 v[100:101], v175 offset:30784
	ds_read_b64_tr_b16 v[104:105], v175 offset:33792
	ds_read_b64_tr_b16 v[106:107], v175 offset:35328
	ds_read_b64_tr_b16 v[110:111], v175 offset:35392
	ds_read_b64_tr_b16 v[108:109], v175 offset:33856
	v_exp_f32_e32 v112, v112
	v_exp_f32_e32 v212, v113
	v_exp_f32_e32 v114, v114
	v_exp_f32_e32 v214, v115
	v_mfma_f32_32x32x16_bf16 v[48:63], v[68:71], v[134:137], v[48:63]
	v_exp_f32_e32 v113, v120
	v_exp_f32_e32 v213, v121
	v_exp_f32_e32 v115, v122
	v_exp_f32_e32 v215, v123
	v_exp_f32_e32 v116, v116
	v_exp_f32_e32 v216, v117
	v_exp_f32_e32 v118, v118
	s_waitcnt lgkmcnt(9)
	v_mfma_f32_32x32x16_bf16 v[80:95], v[178:181], v[138:141], v[80:95]
	v_exp_f32_e32 v218, v119
	v_exp_f32_e32 v117, v124
	v_exp_f32_e32 v217, v125
	v_exp_f32_e32 v119, v126
	v_exp_f32_e32 v219, v127
	v_pk_add_f32 v[120:121], v[208:209], v[210:211]
	s_and_b64 vcc, exec, s[2:3]
	v_mfma_f32_32x32x16_bf16 v[48:63], v[64:67], v[138:141], v[48:63]
	s_nop 3
	v_mov_b64_e32 v[64:65], v[80:81]
	v_mov_b64_e32 v[66:67], v[82:83]
	v_mov_b64_e32 v[68:69], v[84:85]
	v_mov_b64_e32 v[70:71], v[86:87]
	v_mov_b64_e32 v[72:73], v[88:89]
	v_mov_b64_e32 v[74:75], v[90:91]
	v_mov_b64_e32 v[76:77], v[92:93]
	v_mov_b64_e32 v[78:79], v[94:95]
	v_cvt_pk_bf16_f32 v80, v196, v198
	v_cvt_pk_bf16_f32 v81, v200, v202
	v_cvt_pk_bf16_f32 v82, v204, v206
	v_cvt_pk_bf16_f32 v83, v208, v210
	v_mfma_f32_32x32x16_bf16 v[48:63], v[160:163], v[142:145], v[48:63]
	v_cvt_pk_bf16_f32 v84, v197, v199
	v_cvt_pk_bf16_f32 v85, v201, v203
	v_cvt_pk_bf16_f32 v86, v205, v207
	v_cvt_pk_bf16_f32 v87, v209, v211
	v_cvt_pk_bf16_f32 v88, v112, v212
	v_cvt_pk_bf16_f32 v89, v114, v214
	v_cvt_pk_bf16_f32 v90, v116, v216
	s_waitcnt lgkmcnt(6)
	v_mfma_f32_32x32x16_bf16 v[16:31], v[96:99], v[80:83], v[16:31]
	v_add_f32_e64 v96, v196, v198
	v_add_f32_e64 v97, v197, v199
	v_add_f32_e64 v98, v200, v202
	v_add_f32_e64 v99, v201, v203
	v_cvt_pk_bf16_f32 v91, v118, v218
	v_pk_add_f32 v[96:97], v[96:97], v[98:99]
	v_pk_add_f32 v[98:99], v[204:205], v[206:207]
	v_pk_add_f32 v[96:97], v[96:97], 0 op_sel_hi:[1,0]
	v_pk_add_f32 v[98:99], v[98:99], v[120:121]
	s_waitcnt lgkmcnt(4)
	v_mfma_f32_32x32x16_bf16 v[0:15], v[100:103], v[80:83], v[0:15]
	v_add_f32_e64 v80, v98, 0
	v_add_f32_e64 v81, v99, 0
	v_add_f32_e64 v82, v112, v212
	v_add_f32_e64 v83, v113, v213
	v_add_f32_e64 v98, v114, v214
	v_add_f32_e64 v99, v115, v215
	v_pk_add_f32 v[100:101], v[118:119], v[218:219]
	v_pk_add_f32 v[82:83], v[82:83], v[98:99]
	v_pk_add_f32 v[98:99], v[116:117], v[216:217]
	v_pk_add_f32 v[82:83], v[82:83], v[96:97]
	v_mfma_f32_32x32x16_bf16 v[64:79], v[182:185], v[142:145], v[64:79]
	v_add_f32_e64 v98, v98, v100
	v_add_f32_e64 v99, v99, v101
	v_max3_f32 v97, v48, v49, v50
	v_add_f32_e64 v80, v98, v80
	v_add_f32_e64 v81, v99, v81
	v_cvt_pk_bf16_f32 v92, v113, v213
	v_pk_add_f32 v[80:81], v[82:83], v[80:81]
	v_cvt_pk_bf16_f32 v93, v115, v215
	v_add_f32_e32 v96, v80, v81
	s_waitcnt lgkmcnt(2)
	v_mfma_f32_32x32x16_bf16 v[16:31], v[104:107], v[84:87], v[16:31]
	ds_read_b64_tr_b16 v[80:81], v175 offset:36864
	ds_read_b64_tr_b16 v[82:83], v175 offset:38400
	v_max3_f32 v99, v64, v65, v66
	v_max3_f32 v100, v67, v68, v69
	v_cvt_pk_bf16_f32 v94, v117, v217
	v_cvt_pk_bf16_f32 v95, v119, v219
	v_add_f32_e32 v176, v176, v96
	s_waitcnt lgkmcnt(2)
	v_mfma_f32_32x32x16_bf16 v[0:15], v[108:111], v[84:87], v[0:15]
	v_max_f32_e32 v84, v52, v52
	v_max_f32_e32 v85, v51, v51
	v_max_f32_e32 v98, v85, v84
	ds_read_b64_tr_b16 v[86:87], v175 offset:38464
	ds_read_b64_tr_b16 v[84:85], v175 offset:36928
	s_waitcnt lgkmcnt(2)
	v_mfma_f32_32x32x16_bf16 v[16:31], v[80:83], v[88:91], v[16:31]
	v_max3_f32 v80, v97, v54, v55
	v_max3_f32 v97, v98, v53, v56
	v_max3_f32 v98, v99, v70, v71
	v_max3_f32 v99, v100, v72, v73
	v_max3_f32 v100, v80, v58, v59
	ds_read_b64_tr_b16 v[80:81], v175 offset:39936
	ds_read_b64_tr_b16 v[82:83], v175 offset:41472
	s_waitcnt lgkmcnt(2)
	v_mfma_f32_32x32x16_bf16 v[0:15], v[84:87], v[88:91], v[0:15]
	v_max3_f32 v84, v98, v74, v75
	v_max3_f32 v91, v84, v78, v79
	ds_read_b64_tr_b16 v[86:87], v175 offset:41536
	ds_read_b64_tr_b16 v[84:85], v175 offset:40000
	v_max3_f32 v88, v97, v57, v60
	v_max3_f32 v89, v99, v76, v77
	v_max3_f32 v90, v100, v62, v63
	s_waitcnt lgkmcnt(2)
	v_mfma_f32_32x32x16_bf16 v[16:31], v[80:83], v[92:95], v[16:31]
	v_max3_f32 v80, v88, v61, v89
	v_max3_f32 v80, v90, v91, v80
	v_mov_b32_e32 v81, v80
	s_nop 1
	v_permlane32_swap_b32_e32 v80, v81
	s_waitcnt lgkmcnt(0)
	v_mfma_f32_32x32x16_bf16 v[0:15], v[84:87], v[92:95], v[0:15]
	s_cbranch_vccnz .LBB0_1766
	v_max_f32_e32 v80, v80, v80
	v_max_f32_e32 v81, v81, v81
	v_max_f32_e32 v80, v80, v81
	v_cmp_lt_f32_e32 vcc, s51, v80
	s_cbranch_vccnz .LBB0_1771

.LBB0_1850:
	ds_read_b128 v[80:83], v203 offset:13312
	ds_read_b128 v[84:87], v203 offset:13344
	s_waitcnt vmcnt(0)
	ds_read_b128 v[164:167], v203 offset:19968
	ds_read_b128 v[208:211], v203 offset:20000
	ds_read_b128 v[212:215], v203 offset:13376
	v_lshl_add_u64 v[184:185], s[74:75], 0, v[182:183]
	s_waitcnt lgkmcnt(4)
	v_mfma_f32_32x32x16_bf16 v[96:111], v[80:83], v[140:143], v[32:47]
	ds_read_b128 v[216:219], v203 offset:13408
	v_exp_f32_e32 v220, v48
	v_exp_f32_e32 v222, v49
	v_exp_f32_e32 v224, v50
	v_exp_f32_e32 v226, v51
	ds_read_b128 v[48:51], v203 offset:20064
	v_exp_f32_e32 v228, v52
	s_waitcnt lgkmcnt(4)
	v_mfma_f32_32x32x16_bf16 v[112:127], v[164:167], v[140:143], v[32:47]
	v_add_co_u32_e32 v164, vcc, 0xf588000, v184
	v_exp_f32_e32 v230, v53
	s_nop 0
	v_addc_co_u32_e32 v165, vcc, 0, v185, vcc
	global_load_dwordx4 v[164:167], v[164:165], off offset:1664
	v_exp_f32_e32 v232, v54
	v_mfma_f32_32x32x16_bf16 v[96:111], v[84:87], v[144:147], v[96:111]
	v_exp_f32_e32 v234, v55
	v_exp_f32_e32 v221, v56
	v_exp_f32_e32 v223, v57
	v_exp_f32_e32 v225, v58
	v_exp_f32_e32 v227, v59
	v_exp_f32_e32 v229, v60
	v_exp_f32_e32 v231, v61
	s_waitcnt lgkmcnt(2)
	v_mfma_f32_32x32x16_bf16 v[96:111], v[212:215], v[148:151], v[96:111]
	ds_read_b128 v[212:215], v203 offset:20032
	ds_read_b128 v[52:55], v203 offset:13440
	ds_read_b128 v[56:59], v203 offset:13472
	v_exp_f32_e32 v233, v62
	v_exp_f32_e32 v235, v63
	v_exp_f32_e32 v236, v68
	v_exp_f32_e32 v238, v69
	v_exp_f32_e32 v240, v70
	v_mfma_f32_32x32x16_bf16 v[112:127], v[208:211], v[144:147], v[112:127]
	ds_read_b128 v[60:63], v203 offset:20096
	ds_read_b128 v[208:211], v203 offset:20128
	v_exp_f32_e32 v242, v71
	v_cvt_pk_bf16_f32 v68, v220, v222
	v_cvt_pk_bf16_f32 v69, v224, v226
	v_cvt_pk_bf16_f32 v70, v228, v230
	v_cvt_pk_bf16_f32 v71, v232, v234
	v_exp_f32_e32 v237, v76
	s_waitcnt lgkmcnt(4)
	v_mfma_f32_32x32x16_bf16 v[112:127], v[212:215], v[148:151], v[112:127]
	v_exp_f32_e32 v212, v64
	v_exp_f32_e32 v214, v65
	v_exp_f32_e32 v213, v72
	v_exp_f32_e32 v215, v73
	v_exp_f32_e32 v239, v77
	v_exp_f32_e32 v241, v78
	v_exp_f32_e32 v243, v79
	v_mfma_f32_32x32x16_bf16 v[96:111], v[216:219], v[152:155], v[96:111]
	v_exp_f32_e32 v216, v66
	v_exp_f32_e32 v218, v67
	v_exp_f32_e32 v217, v74
	v_exp_f32_e32 v219, v75
	v_cvt_pk_bf16_f32 v72, v221, v223
	v_cvt_pk_bf16_f32 v73, v225, v227
	v_cvt_pk_bf16_f32 v74, v229, v231
	v_mfma_f32_32x32x16_bf16 v[112:127], v[48:51], v[152:155], v[112:127]
	v_cvt_pk_bf16_f32 v75, v233, v235
	v_cvt_pk_bf16_f32 v76, v213, v215
	v_cvt_pk_bf16_f32 v77, v217, v219
	v_cvt_pk_bf16_f32 v78, v237, v239
	v_cvt_pk_bf16_f32 v79, v241, v243
	s_waitcnt lgkmcnt(3)
	v_mfma_f32_32x32x16_bf16 v[96:111], v[52:55], v[156:159], v[96:111]
	ds_read_b64_tr_b16 v[48:49], v175 offset:26624
	ds_read_b64_tr_b16 v[50:51], v175 offset:28160
	ds_read_b64_tr_b16 v[54:55], v175 offset:28224
	ds_read_b64_tr_b16 v[52:53], v175 offset:26688
	s_waitcnt lgkmcnt(5)
	v_mfma_f32_32x32x16_bf16 v[112:127], v[60:63], v[156:159], v[112:127]
	ds_read_b64_tr_b16 v[60:61], v175 offset:29696
	ds_read_b64_tr_b16 v[62:63], v175 offset:31232
	ds_read_b64_tr_b16 v[66:67], v175 offset:31296
	ds_read_b64_tr_b16 v[64:65], v175 offset:29760
	s_waitcnt lgkmcnt(6)
	v_mfma_f32_32x32x16_bf16 v[16:31], v[48:51], v[68:71], v[16:31]
	v_add_f32_e64 v48, v228, v230
	v_add_f32_e64 v49, v229, v231
	v_add_f32_e64 v50, v232, v234
	v_add_f32_e64 v51, v233, v235
	v_add_f32_e64 v48, v48, v50
	v_add_f32_e64 v49, v49, v51
	v_pk_add_f32 v[48:49], v[48:49], 0 op_sel_hi:[1,0]
	s_waitcnt lgkmcnt(4)
	v_mfma_f32_32x32x16_bf16 v[0:15], v[52:55], v[68:71], v[0:15]
	v_add_f32_e64 v54, v236, v238
	v_add_f32_e64 v55, v237, v239
	v_add_f32_e64 v68, v240, v242
	v_add_f32_e64 v69, v241, v243
	v_add_f32_e64 v54, v54, v68
	v_add_f32_e64 v55, v55, v69
	v_pk_add_f32 v[48:49], v[48:49], v[54:55]
	v_mfma_f32_32x32x16_bf16 v[96:111], v[56:59], v[160:163], v[96:111]
	v_cvt_pk_bf16_f32 v56, v212, v214
	v_cvt_pk_bf16_f32 v57, v216, v218
	v_cvt_pk_bf16_f32 v58, v236, v238
	v_cvt_pk_bf16_f32 v59, v240, v242
	v_mfma_f32_32x32x16_bf16 v[112:127], v[208:211], v[160:163], v[112:127]
	v_add_f32_e64 v208, v220, v222
	v_add_f32_e64 v209, v221, v223
	v_add_f32_e64 v210, v224, v226
	v_add_f32_e64 v211, v225, v227
	v_add_f32_e64 v208, v208, v210
	v_add_f32_e64 v209, v209, v211
	v_pk_add_f32 v[210:211], v[216:217], v[218:219]
	v_pk_add_f32 v[50:51], v[208:209], 0 op_sel_hi:[1,0]
	v_pk_add_f32 v[208:209], v[212:213], v[214:215]
	s_waitcnt lgkmcnt(2)
	v_mfma_f32_32x32x16_bf16 v[16:31], v[60:63], v[72:75], v[16:31]
	v_add_f32_e64 v52, v208, v210
	v_add_f32_e64 v53, v209, v211
	v_max3_f32 v54, v112, v113, v114
	v_add_f32_e64 v50, v50, v52
	v_add_f32_e64 v51, v51, v53
	v_max3_f32 v52, v96, v97, v98
	v_pk_add_f32 v[48:49], v[50:51], v[48:49]
	v_max3_f32 v62, v52, v102, v103
	v_add_f32_e32 v60, v48, v49
	s_waitcnt lgkmcnt(0)
	v_mfma_f32_32x32x16_bf16 v[0:15], v[64:67], v[72:75], v[0:15]
	v_max_f32_e32 v48, v100, v100
	v_max_f32_e32 v49, v99, v99
	v_max_f32_e32 v53, v49, v48
	ds_read_b64_tr_b16 v[48:49], v175 offset:32768
	ds_read_b64_tr_b16 v[50:51], v175 offset:34304
	v_max3_f32 v63, v53, v101, v104
	v_max3_f32 v64, v54, v118, v119
	ds_read_b64_tr_b16 v[54:55], v175 offset:34368
	ds_read_b64_tr_b16 v[52:53], v175 offset:32832
	v_max3_f32 v61, v115, v116, v117
	s_waitcnt lgkmcnt(2)
	v_mfma_f32_32x32x16_bf16 v[16:31], v[48:51], v[56:59], v[16:31]
	v_max3_f32 v48, v61, v120, v121
	v_max3_f32 v61, v62, v106, v107
	v_max3_f32 v62, v63, v105, v108
	v_max3_f32 v63, v64, v122, v123
	v_max3_f32 v64, v48, v124, v125
	ds_read_b64_tr_b16 v[48:49], v175 offset:35840
	ds_read_b64_tr_b16 v[50:51], v175 offset:37376
	v_add_f32_e32 v206, v206, v60
	s_waitcnt lgkmcnt(2)
	v_mfma_f32_32x32x16_bf16 v[0:15], v[52:55], v[56:59], v[0:15]
	v_max3_f32 v52, v61, v110, v111
	v_max3_f32 v53, v63, v126, v127
	v_max3_f32 v54, v62, v109, v64
	v_max3_f32 v56, v52, v53, v54
	ds_read_b64_tr_b16 v[54:55], v175 offset:37440
	ds_read_b64_tr_b16 v[52:53], v175 offset:35904
	v_mov_b32_e32 v57, v56
	s_nop 1
	v_permlane32_swap_b32_e32 v56, v57
	s_waitcnt lgkmcnt(2)
	v_mfma_f32_32x32x16_bf16 v[16:31], v[48:51], v[76:79], v[16:31]
	v_max_f32_e32 v48, v57, v57
	v_max_f32_e32 v49, v56, v56
	v_max_f32_e32 v48, v49, v48
	v_cmp_lt_f32_e32 vcc, s51, v48
	s_waitcnt lgkmcnt(0)
	v_mfma_f32_32x32x16_bf16 v[0:15], v[52:55], v[76:79], v[0:15]
	s_cbranch_vccnz .LBB0_1879
	v_cndmask_b32_e64 v48, 0, 1, s[40:41]
	v_cmp_ne_u32_e64 s[8:9], 1, v48
	s_andn2_b64 vcc, exec, s[40:41]
	s_cbranch_vccnz .LBB0_1855

.LBB0_1869:
	ds_read_b128 v[64:67], v203
	ds_read_b128 v[68:71], v203 offset:32
	v_exp_f32_e32 v184, v96
	v_exp_f32_e32 v208, v97
	v_exp_f32_e32 v210, v98
	s_waitcnt lgkmcnt(1)
	v_mfma_f32_32x32x16_bf16 v[48:63], v[64:67], v[140:143], v[32:47]
	v_exp_f32_e32 v212, v99
	v_exp_f32_e32 v214, v100
	v_exp_f32_e32 v216, v101
	v_exp_f32_e32 v218, v102
	v_exp_f32_e32 v220, v103
	v_exp_f32_e32 v185, v104
	v_exp_f32_e32 v209, v105
	s_waitcnt lgkmcnt(0)
	v_mfma_f32_32x32x16_bf16 v[48:63], v[68:71], v[144:147], v[48:63]
	ds_read_b128 v[64:67], v203 offset:6656
	ds_read_b128 v[68:71], v203 offset:6688
	v_exp_f32_e32 v211, v106
	v_exp_f32_e32 v213, v107
	v_exp_f32_e32 v215, v108
	v_exp_f32_e32 v217, v109
	v_exp_f32_e32 v219, v110
	v_exp_f32_e32 v221, v111
	s_waitcnt lgkmcnt(1)
	v_mfma_f32_32x32x16_bf16 v[80:95], v[64:67], v[140:143], v[32:47]
	ds_read_b128 v[64:67], v203 offset:64
	ds_read_b128 v[72:75], v203 offset:96
	v_exp_f32_e32 v222, v112
	v_exp_f32_e32 v224, v113
	v_exp_f32_e32 v226, v114
	v_exp_f32_e32 v228, v115
	v_exp_f32_e32 v230, v116
	v_exp_f32_e32 v232, v117
	s_waitcnt lgkmcnt(1)
	v_mfma_f32_32x32x16_bf16 v[48:63], v[64:67], v[148:151], v[48:63]
	ds_read_b128 v[64:67], v203 offset:6720
	v_exp_f32_e32 v234, v118
	v_exp_f32_e32 v236, v119
	v_exp_f32_e32 v223, v120
	v_exp_f32_e32 v225, v121
	v_exp_f32_e32 v227, v122
	v_exp_f32_e32 v229, v123
	v_mfma_f32_32x32x16_bf16 v[80:95], v[68:71], v[144:147], v[80:95]
	ds_read_b128 v[68:71], v203 offset:6752
	v_exp_f32_e32 v231, v124
	v_exp_f32_e32 v233, v125
	v_exp_f32_e32 v235, v126
	v_exp_f32_e32 v237, v127
	s_and_b64 vcc, exec, s[8:9]
	s_waitcnt lgkmcnt(1)
	v_mfma_f32_32x32x16_bf16 v[80:95], v[64:67], v[148:151], v[80:95]
	s_waitcnt lgkmcnt(0)
	v_mfma_f32_32x32x16_bf16 v[80:95], v[68:71], v[152:155], v[80:95]
	v_mfma_f32_32x32x16_bf16 v[48:63], v[72:75], v[152:155], v[48:63]
	ds_read_b128 v[64:67], v203 offset:128
	ds_read_b128 v[96:99], v203 offset:160
	ds_read_b128 v[72:75], v203 offset:6784
	ds_read_b128 v[100:103], v203 offset:6816
	ds_read_b64_tr_b16 v[104:105], v175 offset:38912
	ds_read_b64_tr_b16 v[106:107], v175 offset:40448
	ds_read_b64_tr_b16 v[110:111], v175 offset:40512
	ds_read_b64_tr_b16 v[108:109], v175 offset:38976
	ds_read_b64_tr_b16 v[112:113], v175 offset:41984
	ds_read_b64_tr_b16 v[114:115], v175 offset:43520
	ds_read_b64_tr_b16 v[118:119], v175 offset:43584
	ds_read_b64_tr_b16 v[116:117], v175 offset:42048
	s_waitcnt lgkmcnt(9)
	v_mfma_f32_32x32x16_bf16 v[80:95], v[72:75], v[156:159], v[80:95]
	v_mfma_f32_32x32x16_bf16 v[48:63], v[64:67], v[156:159], v[48:63]
	s_nop 10
	v_mov_b64_e32 v[64:65], v[80:81]
	v_mov_b64_e32 v[66:67], v[82:83]
	v_mov_b64_e32 v[68:69], v[84:85]
	v_mov_b64_e32 v[70:71], v[86:87]
	v_mov_b64_e32 v[72:73], v[88:89]
	v_mov_b64_e32 v[74:75], v[90:91]
	v_mov_b64_e32 v[76:77], v[92:93]
	v_mov_b64_e32 v[78:79], v[94:95]
	v_cvt_pk_bf16_f32 v80, v184, v208
	v_cvt_pk_bf16_f32 v81, v210, v212
	v_cvt_pk_bf16_f32 v82, v214, v216
	v_cvt_pk_bf16_f32 v83, v218, v220
	v_mfma_f32_32x32x16_bf16 v[48:63], v[96:99], v[160:163], v[48:63]
	v_add_f32_e64 v96, v184, v208
	v_add_f32_e64 v97, v185, v209
	v_add_f32_e64 v98, v210, v212
	v_add_f32_e64 v99, v211, v213
	v_cvt_pk_bf16_f32 v84, v185, v209
	v_pk_add_f32 v[96:97], v[96:97], v[98:99]
	v_pk_add_f32 v[98:99], v[214:215], v[216:217]
	v_cvt_pk_bf16_f32 v85, v211, v213
	v_cvt_pk_bf16_f32 v86, v215, v217
	s_waitcnt lgkmcnt(6)
	v_mfma_f32_32x32x16_bf16 v[16:31], v[104:107], v[80:83], v[16:31]
	v_cvt_pk_bf16_f32 v87, v219, v221
	v_add_f32_e64 v96, v96, 0
	v_add_f32_e64 v97, v97, 0
	v_cvt_pk_bf16_f32 v88, v222, v224
	v_cvt_pk_bf16_f32 v89, v226, v228
	v_cvt_pk_bf16_f32 v90, v230, v232
	v_cvt_pk_bf16_f32 v91, v234, v236
	v_cvt_pk_bf16_f32 v92, v223, v225
	s_waitcnt lgkmcnt(4)
	v_mfma_f32_32x32x16_bf16 v[0:15], v[108:111], v[80:83], v[0:15]
	v_add_f32_e64 v82, v222, v224
	v_add_f32_e64 v83, v223, v225
	v_cvt_pk_bf16_f32 v93, v227, v229
	v_cvt_pk_bf16_f32 v94, v231, v233
	v_cvt_pk_bf16_f32 v95, v235, v237
	v_mfma_f32_32x32x16_bf16 v[64:79], v[100:103], v[160:163], v[64:79]
	v_add_f32_e64 v100, v218, v220
	v_add_f32_e64 v101, v219, v221
	v_add_f32_e64 v98, v98, v100
	v_add_f32_e64 v99, v99, v101
	v_add_f32_e64 v100, v234, v236
	v_add_f32_e64 v101, v235, v237
	v_pk_add_f32 v[80:81], v[98:99], 0 op_sel_hi:[1,0]
	v_pk_add_f32 v[98:99], v[226:227], v[228:229]
	s_nop 0
	v_pk_add_f32 v[82:83], v[82:83], v[98:99]
	v_pk_add_f32 v[98:99], v[230:231], v[232:233]
	s_waitcnt lgkmcnt(2)
	v_mfma_f32_32x32x16_bf16 v[16:31], v[112:115], v[84:87], v[16:31]
	v_add_f32_e64 v98, v98, v100
	v_add_f32_e64 v99, v99, v101
	v_add_f32_e64 v82, v82, v96
	v_add_f32_e64 v83, v83, v97
	v_add_f32_e64 v80, v98, v80
	v_add_f32_e64 v81, v99, v81
	v_max3_f32 v97, v48, v49, v50
	v_pk_add_f32 v[80:81], v[82:83], v[80:81]
	v_max3_f32 v99, v64, v65, v66
	v_add_f32_e32 v96, v80, v81
	s_waitcnt lgkmcnt(0)
	v_mfma_f32_32x32x16_bf16 v[0:15], v[116:119], v[84:87], v[0:15]
	v_max_f32_e32 v84, v52, v52
	v_max_f32_e32 v85, v51, v51
	ds_read_b64_tr_b16 v[80:81], v175 offset:45056
	ds_read_b64_tr_b16 v[82:83], v175 offset:46592
	v_max_f32_e32 v98, v85, v84
	ds_read_b64_tr_b16 v[86:87], v175 offset:46656
	ds_read_b64_tr_b16 v[84:85], v175 offset:45120
	v_max3_f32 v100, v67, v68, v69
	v_add_f32_e32 v206, v206, v96
	s_waitcnt lgkmcnt(2)
	v_mfma_f32_32x32x16_bf16 v[16:31], v[80:83], v[88:91], v[16:31]
	v_max3_f32 v80, v97, v54, v55
	v_max3_f32 v97, v98, v53, v56
	v_max3_f32 v98, v99, v70, v71
	v_max3_f32 v99, v100, v72, v73
	v_max3_f32 v100, v80, v58, v59
	ds_read_b64_tr_b16 v[80:81], v175 offset:48128
	ds_read_b64_tr_b16 v[82:83], v175 offset:49664
	s_waitcnt lgkmcnt(2)
	v_mfma_f32_32x32x16_bf16 v[0:15], v[84:87], v[88:91], v[0:15]
	v_max3_f32 v84, v98, v74, v75
	v_max3_f32 v91, v84, v78, v79
	ds_read_b64_tr_b16 v[86:87], v175 offset:49728
	ds_read_b64_tr_b16 v[84:85], v175 offset:48192
	v_max3_f32 v88, v97, v57, v60
	v_max3_f32 v89, v99, v76, v77
	v_max3_f32 v90, v100, v62, v63
	s_waitcnt lgkmcnt(2)
	v_mfma_f32_32x32x16_bf16 v[16:31], v[80:83], v[92:95], v[16:31]
	v_max3_f32 v80, v88, v61, v89
	v_max3_f32 v80, v90, v91, v80
	v_mov_b32_e32 v81, v80
	s_nop 1
	v_permlane32_swap_b32_e32 v80, v81
	s_waitcnt lgkmcnt(0)
	v_mfma_f32_32x32x16_bf16 v[0:15], v[84:87], v[92:95], v[0:15]
	s_cbranch_vccnz .LBB0_1871
	v_max_f32_e32 v80, v80, v80
	v_max_f32_e32 v81, v81, v81
	v_max_f32_e32 v80, v80, v81
	v_cmp_lt_f32_e32 vcc, s51, v80
	s_cbranch_vccnz .LBB0_1880
